# combination: scale loads at tile header + counted epilogue wait, counted wait in phase-0 row pass, barrier waiters poll the arrival word, phase-10 rows high-to-low
# baseline (speedup 1.0000x reference)
.LBB0_295:
	v_lshl_add_u32 v234, s36, 8, v152
	v_ashrrev_i32_e32 v235, 31, v234
	v_lshl_add_u64 v[234:235], v[234:235], 2, s[18:19]
	s_waitcnt lgkmcnt(0)
	global_load_dword v226, v[234:235], off
	global_load_dword v227, v[234:235], off offset:64
	global_load_dword v228, v[234:235], off offset:128
	global_load_dword v229, v[234:235], off offset:192
	global_load_dword v230, v[234:235], off offset:512
	global_load_dword v231, v[234:235], off offset:576
	global_load_dword v232, v[234:235], off offset:640
	global_load_dword v233, v[234:235], off offset:704
	s_add_i32 s49, s49, 1
	s_mul_i32 s4, s49, s52
	s_mul_hi_u32 s5, s49, s53
	s_add_i32 s5, s5, s4
	s_mul_i32 s4, s49, s53
	s_add_u32 s28, s4, s2
	s_addc_u32 s29, s5, s3
	v_cmp_gt_i64_e32 vcc, s[28:29], v[142:143]
	v_cmp_lt_i64_e64 s[4:5], s[28:29], v[140:141]
	s_cbranch_vccnz .LBB0_301
	s_ashr_i32 s24, s28, 31
	s_lshr_b32 s24, s24, 29
	s_add_i32 s26, s28, s24
	s_and_b32 s24, s26, -8
	s_sub_i32 s27, s28, s24
	s_cmp_gt_i32 s27, 3
	s_mov_b64 s[24:25], -1
	s_cbranch_scc0 .LBB0_298
	s_mul_i32 s24, s27, 0xf7
	s_add_i32 s28, s24, 4
	s_mov_b64 s[24:25], 0

.LBB0_305:
	v_lshl_add_u32 v144, s36, 8, v152
	v_ashrrev_i32_e32 v145, 31, v144
	v_lshl_add_u64 v[148:149], v[144:145], 2, s[18:19]
	s_waitcnt lgkmcnt(0)
	v_lshl_or_b32 v150, s57, 8, v154
	v_mov_b64_e32 v[146:147], s[16:17]
	v_ashrrev_i32_e32 v151, 31, v150
	v_mad_i64_i32 v[162:163], s[38:39], v144, s56, v[146:147]
	v_or_b32_e32 v164, 16, v144
	v_lshlrev_b64 v[150:151], 1, v[150:151]
	v_ashrrev_i32_e32 v165, 31, v164
	v_lshl_add_u64 v[162:163], v[162:163], 0, v[150:151]
	v_lshl_add_u64 v[166:167], v[164:165], 2, s[18:19]
	s_andn2_b64 vcc, exec, s[4:5]
	s_mov_b64 s[4:5], -1
	s_waitcnt vmcnt(16)
	v_mov_b32_e32 v160, v226
	v_pk_mul_f32 v[126:127], v[126:127], v[160:161] op_sel_hi:[1,0]
	v_pk_mul_f32 v[124:125], v[124:125], v[160:161] op_sel_hi:[1,0]
	v_pk_mul_f32 v[122:123], v[122:123], v[160:161] op_sel_hi:[1,0]
	v_pk_mul_f32 v[120:121], v[120:121], v[160:161] op_sel_hi:[1,0]
	v_pk_mul_f32 v[118:119], v[118:119], v[160:161] op_sel_hi:[1,0]
	v_pk_mul_f32 v[116:117], v[116:117], v[160:161] op_sel_hi:[1,0]
	v_pk_mul_f32 v[168:169], v[114:115], v[160:161] op_sel_hi:[1,0]
	v_pk_mul_f32 v[160:161], v[112:113], v[160:161] op_sel_hi:[1,0]
	v_cvt_pk_bf16_f32 v112, v124, v125
	v_cvt_pk_bf16_f32 v113, v126, v127
	v_cvt_pk_bf16_f32 v114, v120, v121
	v_cvt_pk_bf16_f32 v115, v122, v123
	global_store_dwordx4 v[162:163], v[112:115], off
	s_nop 1
	v_cvt_pk_bf16_f32 v112, v116, v117
	v_cvt_pk_bf16_f32 v113, v118, v119
	v_cvt_pk_bf16_f32 v114, v160, v161
	v_cvt_pk_bf16_f32 v115, v168, v169
	global_store_dwordx4 v[162:163], v[112:115], off offset:256
	s_nop 1
	v_mad_i64_i32 v[116:117], s[38:39], v164, s56, v[146:147]
	v_or_b32_e32 v114, 32, v144
	v_ashrrev_i32_e32 v115, 31, v114
	v_lshl_add_u64 v[116:117], v[116:117], 0, v[150:151]
	v_lshl_add_u64 v[118:119], v[114:115], 2, s[18:19]
	v_mov_b32_e32 v112, v227
	v_pk_mul_f32 v[110:111], v[110:111], v[112:113] op_sel_hi:[1,0]
	v_pk_mul_f32 v[108:109], v[108:109], v[112:113] op_sel_hi:[1,0]
	v_pk_mul_f32 v[106:107], v[106:107], v[112:113] op_sel_hi:[1,0]
	v_pk_mul_f32 v[104:105], v[104:105], v[112:113] op_sel_hi:[1,0]
	v_pk_mul_f32 v[102:103], v[102:103], v[112:113] op_sel_hi:[1,0]
	v_pk_mul_f32 v[100:101], v[100:101], v[112:113] op_sel_hi:[1,0]
	v_pk_mul_f32 v[120:121], v[98:99], v[112:113] op_sel_hi:[1,0]
	v_pk_mul_f32 v[112:113], v[96:97], v[112:113] op_sel_hi:[1,0]
	v_cvt_pk_bf16_f32 v96, v108, v109
	v_cvt_pk_bf16_f32 v97, v110, v111
	v_cvt_pk_bf16_f32 v98, v104, v105
	v_cvt_pk_bf16_f32 v99, v106, v107
	global_store_dwordx4 v[116:117], v[96:99], off
	s_nop 1
	v_cvt_pk_bf16_f32 v96, v100, v101
	v_cvt_pk_bf16_f32 v97, v102, v103
	v_cvt_pk_bf16_f32 v98, v112, v113
	v_cvt_pk_bf16_f32 v99, v120, v121
	global_store_dwordx4 v[116:117], v[96:99], off offset:256
	s_nop 1
	v_mad_i64_i32 v[100:101], s[38:39], v114, s56, v[146:147]
	v_or_b32_e32 v98, 48, v144
	v_ashrrev_i32_e32 v99, 31, v98
	v_lshl_add_u64 v[100:101], v[100:101], 0, v[150:151]
	v_lshl_add_u64 v[102:103], v[98:99], 2, s[18:19]
	v_mov_b32_e32 v96, v228
	v_pk_mul_f32 v[94:95], v[94:95], v[96:97] op_sel_hi:[1,0]
	v_pk_mul_f32 v[92:93], v[92:93], v[96:97] op_sel_hi:[1,0]
	v_pk_mul_f32 v[90:91], v[90:91], v[96:97] op_sel_hi:[1,0]
	v_pk_mul_f32 v[88:89], v[88:89], v[96:97] op_sel_hi:[1,0]
	v_pk_mul_f32 v[82:83], v[82:83], v[96:97] op_sel_hi:[1,0]
	v_pk_mul_f32 v[80:81], v[80:81], v[96:97] op_sel_hi:[1,0]
	v_pk_mul_f32 v[104:105], v[74:75], v[96:97] op_sel_hi:[1,0]
	v_pk_mul_f32 v[96:97], v[72:73], v[96:97] op_sel_hi:[1,0]
	v_cvt_pk_bf16_f32 v72, v92, v93
	v_cvt_pk_bf16_f32 v73, v94, v95
	v_cvt_pk_bf16_f32 v74, v88, v89
	v_cvt_pk_bf16_f32 v75, v90, v91
	global_store_dwordx4 v[100:101], v[72:75], off
	s_nop 1
	v_cvt_pk_bf16_f32 v72, v80, v81
	v_cvt_pk_bf16_f32 v73, v82, v83
	v_cvt_pk_bf16_f32 v74, v96, v97
	v_cvt_pk_bf16_f32 v75, v104, v105
	global_store_dwordx4 v[100:101], v[72:75], off offset:256
	s_nop 1
	v_mov_b32_e32 v72, v229
	v_pk_mul_f32 v[80:81], v[86:87], v[72:73] op_sel_hi:[1,0]
	v_mad_i64_i32 v[74:75], s[38:39], v98, s56, v[146:147]
	v_lshl_add_u64 v[74:75], v[74:75], 0, v[150:151]
	v_pk_mul_f32 v[82:83], v[84:85], v[72:73] op_sel_hi:[1,0]
	v_pk_mul_f32 v[78:79], v[78:79], v[72:73] op_sel_hi:[1,0]
	v_pk_mul_f32 v[76:77], v[76:77], v[72:73] op_sel_hi:[1,0]
	v_pk_mul_f32 v[70:71], v[70:71], v[72:73] op_sel_hi:[1,0]
	v_pk_mul_f32 v[68:69], v[68:69], v[72:73] op_sel_hi:[1,0]
	v_pk_mul_f32 v[84:85], v[66:67], v[72:73] op_sel_hi:[1,0]
	v_pk_mul_f32 v[72:73], v[64:65], v[72:73] op_sel_hi:[1,0]
	v_cvt_pk_bf16_f32 v64, v82, v83
	v_cvt_pk_bf16_f32 v65, v80, v81
	v_cvt_pk_bf16_f32 v66, v76, v77
	v_cvt_pk_bf16_f32 v67, v78, v79
	global_store_dwordx4 v[74:75], v[64:67], off
	s_nop 1
	v_cvt_pk_bf16_f32 v64, v68, v69
	v_cvt_pk_bf16_f32 v65, v70, v71
	v_cvt_pk_bf16_f32 v66, v72, v73
	v_cvt_pk_bf16_f32 v67, v84, v85
	global_store_dwordx4 v[74:75], v[64:67], off offset:256
	s_nop 1
	s_nop 0
	v_add_u32_e32 v65, 0x80, v144
	v_mad_i64_i32 v[66:67], s[38:39], v65, s56, v[146:147]
	v_lshl_add_u64 v[66:67], v[66:67], 0, v[150:151]
	v_mov_b32_e32 v64, v230
	v_pk_mul_f32 v[62:63], v[62:63], v[64:65] op_sel_hi:[1,0]
	v_pk_mul_f32 v[60:61], v[60:61], v[64:65] op_sel_hi:[1,0]
	v_pk_mul_f32 v[58:59], v[58:59], v[64:65] op_sel_hi:[1,0]
	v_pk_mul_f32 v[56:57], v[56:57], v[64:65] op_sel_hi:[1,0]
	v_pk_mul_f32 v[54:55], v[54:55], v[64:65] op_sel_hi:[1,0]
	v_pk_mul_f32 v[52:53], v[52:53], v[64:65] op_sel_hi:[1,0]
	v_pk_mul_f32 v[68:69], v[50:51], v[64:65] op_sel_hi:[1,0]
	v_pk_mul_f32 v[64:65], v[48:49], v[64:65] op_sel_hi:[1,0]
	v_cvt_pk_bf16_f32 v48, v60, v61
	v_cvt_pk_bf16_f32 v49, v62, v63
	v_cvt_pk_bf16_f32 v50, v56, v57
	v_cvt_pk_bf16_f32 v51, v58, v59
	global_store_dwordx4 v[66:67], v[48:51], off
	s_nop 1
	v_cvt_pk_bf16_f32 v48, v52, v53
	v_cvt_pk_bf16_f32 v49, v54, v55
	v_cvt_pk_bf16_f32 v50, v64, v65
	v_cvt_pk_bf16_f32 v51, v68, v69
	global_store_dwordx4 v[66:67], v[48:51], off offset:256
	s_nop 1
	s_nop 0
	v_add_u32_e32 v49, 0x90, v144
	v_mad_i64_i32 v[50:51], s[38:39], v49, s56, v[146:147]
	v_lshl_add_u64 v[50:51], v[50:51], 0, v[150:151]
	v_mov_b32_e32 v48, v231
	v_pk_mul_f32 v[46:47], v[46:47], v[48:49] op_sel_hi:[1,0]
	v_pk_mul_f32 v[44:45], v[44:45], v[48:49] op_sel_hi:[1,0]
	v_pk_mul_f32 v[42:43], v[42:43], v[48:49] op_sel_hi:[1,0]
	v_pk_mul_f32 v[40:41], v[40:41], v[48:49] op_sel_hi:[1,0]
	v_pk_mul_f32 v[38:39], v[38:39], v[48:49] op_sel_hi:[1,0]
	v_pk_mul_f32 v[36:37], v[36:37], v[48:49] op_sel_hi:[1,0]
	v_pk_mul_f32 v[52:53], v[34:35], v[48:49] op_sel_hi:[1,0]
	v_pk_mul_f32 v[48:49], v[32:33], v[48:49] op_sel_hi:[1,0]
	v_cvt_pk_bf16_f32 v32, v44, v45
	v_cvt_pk_bf16_f32 v33, v46, v47
	v_cvt_pk_bf16_f32 v34, v40, v41
	v_cvt_pk_bf16_f32 v35, v42, v43
	global_store_dwordx4 v[50:51], v[32:35], off
	s_nop 1
	v_cvt_pk_bf16_f32 v32, v36, v37
	v_cvt_pk_bf16_f32 v33, v38, v39
	v_cvt_pk_bf16_f32 v34, v48, v49
	v_cvt_pk_bf16_f32 v35, v52, v53
	global_store_dwordx4 v[50:51], v[32:35], off offset:256
	s_nop 1
	s_nop 0
	v_add_u32_e32 v33, 0xa0, v144
	v_mad_i64_i32 v[34:35], s[38:39], v33, s56, v[146:147]
	v_lshl_add_u64 v[34:35], v[34:35], 0, v[150:151]
	v_mov_b32_e32 v32, v232
	v_pk_mul_f32 v[30:31], v[30:31], v[32:33] op_sel_hi:[1,0]
	v_pk_mul_f32 v[28:29], v[28:29], v[32:33] op_sel_hi:[1,0]
	v_pk_mul_f32 v[26:27], v[26:27], v[32:33] op_sel_hi:[1,0]
	v_pk_mul_f32 v[24:25], v[24:25], v[32:33] op_sel_hi:[1,0]
	v_pk_mul_f32 v[22:23], v[22:23], v[32:33] op_sel_hi:[1,0]
	v_pk_mul_f32 v[20:21], v[20:21], v[32:33] op_sel_hi:[1,0]
	v_pk_mul_f32 v[36:37], v[18:19], v[32:33] op_sel_hi:[1,0]
	v_pk_mul_f32 v[32:33], v[16:17], v[32:33] op_sel_hi:[1,0]
	v_cvt_pk_bf16_f32 v16, v28, v29
	v_cvt_pk_bf16_f32 v17, v30, v31
	v_cvt_pk_bf16_f32 v18, v24, v25
	v_cvt_pk_bf16_f32 v19, v26, v27
	global_store_dwordx4 v[34:35], v[16:19], off
	s_nop 1
	v_cvt_pk_bf16_f32 v16, v20, v21
	v_cvt_pk_bf16_f32 v17, v22, v23
	v_cvt_pk_bf16_f32 v18, v32, v33
	v_cvt_pk_bf16_f32 v19, v36, v37
	global_store_dwordx4 v[34:35], v[16:19], off offset:256
	s_nop 1
	s_nop 0
	v_add_u32_e32 v17, 0xb0, v144
	v_mad_i64_i32 v[18:19], s[38:39], v17, s56, v[146:147]
	v_lshl_add_u64 v[18:19], v[18:19], 0, v[150:151]
	v_mov_b32_e32 v16, v233
	v_pk_mul_f32 v[14:15], v[14:15], v[16:17] op_sel_hi:[1,0]
	v_pk_mul_f32 v[12:13], v[12:13], v[16:17] op_sel_hi:[1,0]
	v_pk_mul_f32 v[10:11], v[10:11], v[16:17] op_sel_hi:[1,0]
	v_pk_mul_f32 v[8:9], v[8:9], v[16:17] op_sel_hi:[1,0]
	v_pk_mul_f32 v[6:7], v[6:7], v[16:17] op_sel_hi:[1,0]
	v_pk_mul_f32 v[4:5], v[4:5], v[16:17] op_sel_hi:[1,0]
	v_pk_mul_f32 v[20:21], v[2:3], v[16:17] op_sel_hi:[1,0]
	v_pk_mul_f32 v[16:17], v[0:1], v[16:17] op_sel_hi:[1,0]
	v_cvt_pk_bf16_f32 v0, v12, v13
	v_cvt_pk_bf16_f32 v1, v14, v15
	v_cvt_pk_bf16_f32 v2, v8, v9
	v_cvt_pk_bf16_f32 v3, v10, v11
	global_store_dwordx4 v[18:19], v[0:3], off
	s_nop 1
	v_cvt_pk_bf16_f32 v0, v4, v5
	v_cvt_pk_bf16_f32 v1, v6, v7
	v_cvt_pk_bf16_f32 v2, v16, v17
	v_cvt_pk_bf16_f32 v3, v20, v21
	global_store_dwordx4 v[18:19], v[0:3], off offset:256
	s_cbranch_vccnz .LBB0_294
	s_andn2_b64 vcc, exec, s[8:9]
	s_cbranch_vccnz .LBB0_293
	s_barrier
	s_branch .LBB0_293

.LBB0_1305:
	v_lshl_add_u32 v234, s36, 8, v148
	v_ashrrev_i32_e32 v235, 31, v234
	v_lshl_add_u64 v[234:235], v[234:235], 2, s[18:19]
	s_waitcnt lgkmcnt(0)
	global_load_dword v226, v[234:235], off
	global_load_dword v227, v[234:235], off offset:64
	global_load_dword v228, v[234:235], off offset:128
	global_load_dword v229, v[234:235], off offset:192
	global_load_dword v230, v[234:235], off offset:512
	global_load_dword v231, v[234:235], off offset:576
	global_load_dword v232, v[234:235], off offset:640
	global_load_dword v233, v[234:235], off offset:704
	s_add_i32 s51, s51, 1
	s_mul_i32 s4, s51, s54
	s_mul_hi_u32 s5, s51, s55
	s_add_i32 s5, s5, s4
	s_mul_i32 s4, s51, s55
	s_add_u32 s28, s4, s2
	s_addc_u32 s29, s5, s3
	v_cmp_gt_i64_e32 vcc, s[28:29], v[142:143]
	v_cmp_lt_i64_e64 s[4:5], s[28:29], v[140:141]
	s_cbranch_vccnz .LBB0_1311
	s_ashr_i32 s24, s28, 31
	s_lshr_b32 s24, s24, 29
	s_add_i32 s26, s28, s24
	s_and_b32 s24, s26, -8
	s_sub_i32 s27, s28, s24
	s_cmp_gt_i32 s27, 3
	s_mov_b64 s[24:25], -1
	s_cbranch_scc0 .LBB0_1308
	s_mul_i32 s24, s27, 0xb5
	s_add_i32 s28, s24, 4
	s_mov_b64 s[24:25], 0

.LBB0_1315:
	v_lshl_add_u32 v144, s36, 8, v148
	v_ashrrev_i32_e32 v145, 31, v144
	v_lshl_add_u64 v[146:147], v[144:145], 2, s[18:19]
	s_waitcnt lgkmcnt(0)
	v_lshl_or_b32 v158, s59, 7, v150
	v_mov_b32_e32 v163, v114
	v_mov_b32_e32 v114, v119
	v_mov_b32_e32 v160, v124
	v_mov_b32_e32 v161, v120
	v_mov_b32_e32 v120, v125
	v_mov_b32_e32 v124, v126
	v_mov_b32_e32 v125, v122
	v_mov_b32_e32 v122, v127
	v_mov_b32_e32 v126, v116
	v_mov_b32_e32 v127, v112
	v_mov_b32_e32 v112, v117
	v_mov_b32_e32 v162, v118
	v_mov_b64_e32 v[116:117], s[16:17]
	v_ashrrev_i32_e32 v159, 31, v158
	v_or_b32_e32 v166, 16, v144
	v_mad_i64_i32 v[164:165], s[38:39], v144, s58, v[116:117]
	v_lshlrev_b64 v[118:119], 1, v[158:159]
	v_ashrrev_i32_e32 v167, 31, v166
	v_lshl_add_u64 v[158:159], v[164:165], 0, v[118:119]
	v_lshl_add_u64 v[164:165], v[166:167], 2, s[18:19]
	s_andn2_b64 vcc, exec, s[4:5]
	s_mov_b64 s[4:5], -1
	s_waitcnt vmcnt(16)
	v_mov_b32_e32 v154, v226
	v_pk_mul_f32 v[114:115], v[114:115], v[154:155] op_sel_hi:[1,0]
	v_pk_mul_f32 v[160:161], v[160:161], v[154:155] op_sel_hi:[1,0]
	v_pk_mul_f32 v[120:121], v[120:121], v[154:155] op_sel_hi:[1,0]
	v_pk_mul_f32 v[124:125], v[124:125], v[154:155] op_sel_hi:[1,0]
	v_pk_mul_f32 v[122:123], v[122:123], v[154:155] op_sel_hi:[1,0]
	v_pk_mul_f32 v[126:127], v[126:127], v[154:155] op_sel_hi:[1,0]
	v_pk_mul_f32 v[112:113], v[112:113], v[154:155] op_sel_hi:[1,0]
	v_pk_mul_f32 v[162:163], v[162:163], v[154:155] op_sel_hi:[1,0]
	v_mul_f32_e32 v170, 0xbfb8aa3b, v115
	v_mul_f32_e32 v145, 0xbfb8aa3b, v161
	v_mul_f32_e32 v154, 0xbfb8aa3b, v121
	v_mul_f32_e32 v155, 0xbfb8aa3b, v125
	v_mul_f32_e32 v157, 0xbfb8aa3b, v123
	v_mul_f32_e32 v167, 0xbfb8aa3b, v127
	v_mul_f32_e32 v168, 0xbfb8aa3b, v113
	v_mul_f32_e32 v169, 0xbfb8aa3b, v163
	v_exp_f32_e32 v170, v170
	v_exp_f32_e32 v145, v145
	v_exp_f32_e32 v154, v154
	v_exp_f32_e32 v155, v155
	v_exp_f32_e32 v157, v157
	v_exp_f32_e32 v167, v167
	v_exp_f32_e32 v168, v168
	v_exp_f32_e32 v169, v169
	v_add_f32_e32 v170, 1.0, v170
	v_add_f32_e32 v145, 1.0, v145
	v_add_f32_e32 v154, 1.0, v154
	v_add_f32_e32 v155, 1.0, v155
	v_add_f32_e32 v157, 1.0, v157
	v_add_f32_e32 v167, 1.0, v167
	v_add_f32_e32 v168, 1.0, v168
	v_add_f32_e32 v169, 1.0, v169
	v_rcp_f32_e32 v170, v170
	v_rcp_f32_e32 v145, v145
	v_rcp_f32_e32 v154, v154
	v_rcp_f32_e32 v155, v155
	v_rcp_f32_e32 v157, v157
	v_rcp_f32_e32 v167, v167
	v_rcp_f32_e32 v168, v168
	v_rcp_f32_e32 v169, v169
	v_mul_f32_e32 v115, v115, v170
	v_mul_f32_e32 v145, v161, v145
	v_mul_f32_e32 v121, v121, v154
	v_mul_f32_e32 v125, v125, v155
	v_mul_f32_e32 v123, v123, v157
	v_mul_f32_e32 v127, v127, v167
	v_mul_f32_e32 v113, v113, v168
	v_mul_f32_e32 v154, v163, v169
	v_mul_f32_e32 v115, v114, v115
	v_mul_f32_e32 v145, v160, v145
	v_mul_f32_e32 v120, v120, v121
	v_mul_f32_e32 v121, v124, v125
	v_mul_f32_e32 v122, v122, v123
	v_mul_f32_e32 v123, v126, v127
	v_mul_f32_e32 v124, v112, v113
	v_mul_f32_e32 v125, v162, v154
	v_cvt_pk_bf16_f32 v112, v145, v120
	v_cvt_pk_bf16_f32 v113, v121, v122
	v_cvt_pk_bf16_f32 v114, v123, v124
	v_cvt_pk_bf16_f32 v115, v125, v115
	global_store_dwordx4 v[158:159], v[112:115], off
	s_nop 1
	v_mad_i64_i32 v[120:121], s[38:39], v166, s58, v[116:117]
	v_mov_b32_e32 v115, v104
	v_mov_b32_e32 v104, v109
	v_mov_b32_e32 v109, v106
	v_mov_b32_e32 v106, v111
	v_mov_b32_e32 v111, v96
	v_mov_b32_e32 v96, v101
	v_mov_b32_e32 v101, v98
	v_mov_b32_e32 v98, v103
	v_mov_b32_e32 v114, v108
	v_mov_b32_e32 v108, v110
	v_mov_b32_e32 v110, v100
	v_mov_b32_e32 v100, v102
	v_or_b32_e32 v102, 32, v144
	v_ashrrev_i32_e32 v103, 31, v102
	v_lshl_add_u64 v[122:123], v[102:103], 2, s[18:19]
	v_lshl_add_u64 v[120:121], v[120:121], 0, v[118:119]
	v_mov_b32_e32 v112, v227
	v_pk_mul_f32 v[98:99], v[98:99], v[112:113] op_sel_hi:[1,0]
	v_pk_mul_f32 v[114:115], v[114:115], v[112:113] op_sel_hi:[1,0]
	v_pk_mul_f32 v[104:105], v[104:105], v[112:113] op_sel_hi:[1,0]
	v_pk_mul_f32 v[108:109], v[108:109], v[112:113] op_sel_hi:[1,0]
	v_pk_mul_f32 v[106:107], v[106:107], v[112:113] op_sel_hi:[1,0]
	v_pk_mul_f32 v[110:111], v[110:111], v[112:113] op_sel_hi:[1,0]
	v_pk_mul_f32 v[96:97], v[96:97], v[112:113] op_sel_hi:[1,0]
	v_pk_mul_f32 v[100:101], v[100:101], v[112:113] op_sel_hi:[1,0]
	v_mul_f32_e32 v145, 0xbfb8aa3b, v99
	v_mul_f32_e32 v103, 0xbfb8aa3b, v115
	v_mul_f32_e32 v112, 0xbfb8aa3b, v105
	v_mul_f32_e32 v113, 0xbfb8aa3b, v109
	v_mul_f32_e32 v124, 0xbfb8aa3b, v107
	v_mul_f32_e32 v125, 0xbfb8aa3b, v111
	v_mul_f32_e32 v126, 0xbfb8aa3b, v97
	v_mul_f32_e32 v127, 0xbfb8aa3b, v101
	v_exp_f32_e32 v145, v145
	v_exp_f32_e32 v103, v103
	v_exp_f32_e32 v112, v112
	v_exp_f32_e32 v113, v113
	v_exp_f32_e32 v124, v124
	v_exp_f32_e32 v125, v125
	v_exp_f32_e32 v126, v126
	v_exp_f32_e32 v127, v127
	v_add_f32_e32 v145, 1.0, v145
	v_add_f32_e32 v103, 1.0, v103
	v_add_f32_e32 v112, 1.0, v112
	v_add_f32_e32 v113, 1.0, v113
	v_add_f32_e32 v124, 1.0, v124
	v_add_f32_e32 v125, 1.0, v125
	v_add_f32_e32 v126, 1.0, v126
	v_add_f32_e32 v127, 1.0, v127
	v_rcp_f32_e32 v145, v145
	v_rcp_f32_e32 v103, v103
	v_rcp_f32_e32 v112, v112
	v_rcp_f32_e32 v113, v113
	v_rcp_f32_e32 v124, v124
	v_rcp_f32_e32 v125, v125
	v_rcp_f32_e32 v126, v126
	v_rcp_f32_e32 v127, v127
	v_mul_f32_e32 v99, v99, v145
	v_mul_f32_e32 v103, v115, v103
	v_mul_f32_e32 v105, v105, v112
	v_mul_f32_e32 v109, v109, v113
	v_mul_f32_e32 v107, v107, v124
	v_mul_f32_e32 v111, v111, v125
	v_mul_f32_e32 v97, v97, v126
	v_mul_f32_e32 v101, v101, v127
	v_mul_f32_e32 v99, v98, v99
	v_mul_f32_e32 v103, v114, v103
	v_mul_f32_e32 v104, v104, v105
	v_mul_f32_e32 v105, v108, v109
	v_mul_f32_e32 v106, v106, v107
	v_mul_f32_e32 v107, v110, v111
	v_mul_f32_e32 v108, v96, v97
	v_mul_f32_e32 v100, v100, v101
	v_cvt_pk_bf16_f32 v96, v103, v104
	v_cvt_pk_bf16_f32 v97, v105, v106
	v_cvt_pk_bf16_f32 v98, v107, v108
	v_cvt_pk_bf16_f32 v99, v100, v99
	global_store_dwordx4 v[120:121], v[96:99], off
	s_nop 1
	v_mad_i64_i32 v[100:101], s[38:39], v102, s58, v[116:117]
	v_mov_b32_e32 v99, v88
	v_mov_b32_e32 v88, v93
	v_mov_b32_e32 v93, v90
	v_mov_b32_e32 v90, v95
	v_mov_b32_e32 v95, v80
	v_mov_b32_e32 v80, v85
	v_mov_b32_e32 v85, v82
	v_mov_b32_e32 v82, v87
	v_mov_b32_e32 v98, v92
	v_mov_b32_e32 v92, v94
	v_mov_b32_e32 v94, v84
	v_mov_b32_e32 v84, v86
	v_or_b32_e32 v86, 48, v144
	v_ashrrev_i32_e32 v87, 31, v86
	v_lshl_add_u64 v[102:103], v[86:87], 2, s[18:19]
	v_lshl_add_u64 v[100:101], v[100:101], 0, v[118:119]
	v_mov_b32_e32 v96, v228
	v_pk_mul_f32 v[82:83], v[82:83], v[96:97] op_sel_hi:[1,0]
	v_pk_mul_f32 v[98:99], v[98:99], v[96:97] op_sel_hi:[1,0]
	v_pk_mul_f32 v[88:89], v[88:89], v[96:97] op_sel_hi:[1,0]
	v_pk_mul_f32 v[92:93], v[92:93], v[96:97] op_sel_hi:[1,0]
	v_pk_mul_f32 v[90:91], v[90:91], v[96:97] op_sel_hi:[1,0]
	v_pk_mul_f32 v[94:95], v[94:95], v[96:97] op_sel_hi:[1,0]
	v_pk_mul_f32 v[80:81], v[80:81], v[96:97] op_sel_hi:[1,0]
	v_pk_mul_f32 v[84:85], v[84:85], v[96:97] op_sel_hi:[1,0]
	v_mul_f32_e32 v108, 0xbfb8aa3b, v83
	v_mul_f32_e32 v87, 0xbfb8aa3b, v99
	v_mul_f32_e32 v96, 0xbfb8aa3b, v89
	v_mul_f32_e32 v97, 0xbfb8aa3b, v93
	v_mul_f32_e32 v104, 0xbfb8aa3b, v91
	v_mul_f32_e32 v105, 0xbfb8aa3b, v95
	v_mul_f32_e32 v106, 0xbfb8aa3b, v81
	v_mul_f32_e32 v107, 0xbfb8aa3b, v85
	v_exp_f32_e32 v108, v108
	v_exp_f32_e32 v87, v87
	v_exp_f32_e32 v96, v96
	v_exp_f32_e32 v97, v97
	v_exp_f32_e32 v104, v104
	v_exp_f32_e32 v105, v105
	v_exp_f32_e32 v106, v106
	v_exp_f32_e32 v107, v107
	v_add_f32_e32 v108, 1.0, v108
	v_add_f32_e32 v87, 1.0, v87
	v_add_f32_e32 v96, 1.0, v96
	v_add_f32_e32 v97, 1.0, v97
	v_add_f32_e32 v104, 1.0, v104
	v_add_f32_e32 v105, 1.0, v105
	v_add_f32_e32 v106, 1.0, v106
	v_add_f32_e32 v107, 1.0, v107
	v_rcp_f32_e32 v108, v108
	v_rcp_f32_e32 v87, v87
	v_rcp_f32_e32 v96, v96
	v_rcp_f32_e32 v97, v97
	v_rcp_f32_e32 v104, v104
	v_rcp_f32_e32 v105, v105
	v_rcp_f32_e32 v106, v106
	v_rcp_f32_e32 v107, v107
	v_mul_f32_e32 v83, v83, v108
	v_mul_f32_e32 v87, v99, v87
	v_mul_f32_e32 v89, v89, v96
	v_mul_f32_e32 v93, v93, v97
	v_mul_f32_e32 v91, v91, v104
	v_mul_f32_e32 v95, v95, v105
	v_mul_f32_e32 v81, v81, v106
	v_mul_f32_e32 v85, v85, v107
	v_mul_f32_e32 v83, v82, v83
	v_mul_f32_e32 v87, v98, v87
	v_mul_f32_e32 v88, v88, v89
	v_mul_f32_e32 v89, v92, v93
	v_mul_f32_e32 v90, v90, v91
	v_mul_f32_e32 v91, v94, v95
	v_mul_f32_e32 v92, v80, v81
	v_mul_f32_e32 v84, v84, v85
	v_cvt_pk_bf16_f32 v80, v87, v88
	v_cvt_pk_bf16_f32 v81, v89, v90
	v_cvt_pk_bf16_f32 v82, v91, v92
	v_cvt_pk_bf16_f32 v83, v84, v83
	global_store_dwordx4 v[100:101], v[80:83], off
	s_nop 1
	s_nop 0
	v_mov_b32_e32 v82, v76
	v_mov_b32_e32 v83, v72
	v_mov_b32_e32 v72, v77
	v_mov_b32_e32 v76, v78
	v_mov_b32_e32 v77, v74
	v_mov_b32_e32 v74, v79
	v_mov_b32_e32 v78, v64
	v_mov_b32_e32 v79, v68
	v_mov_b32_e32 v68, v65
	v_mov_b32_e32 v64, v66
	v_mov_b32_e32 v65, v70
	v_mov_b32_e32 v70, v67
	v_mad_i64_i32 v[66:67], s[38:39], v86, s58, v[116:117]
	v_lshl_add_u64 v[84:85], v[66:67], 0, v[118:119]
	v_mov_b32_e32 v80, v229
	v_pk_mul_f32 v[66:67], v[82:83], v[80:81] op_sel_hi:[1,0]
	v_pk_mul_f32 v[72:73], v[72:73], v[80:81] op_sel_hi:[1,0]
	v_pk_mul_f32 v[76:77], v[76:77], v[80:81] op_sel_hi:[1,0]
	v_pk_mul_f32 v[74:75], v[74:75], v[80:81] op_sel_hi:[1,0]
	v_pk_mul_f32 v[78:79], v[78:79], v[80:81] op_sel_hi:[1,0]
	v_pk_mul_f32 v[68:69], v[68:69], v[80:81] op_sel_hi:[1,0]
	v_pk_mul_f32 v[64:65], v[64:65], v[80:81] op_sel_hi:[1,0]
	v_pk_mul_f32 v[70:71], v[70:71], v[80:81] op_sel_hi:[1,0]
	v_mul_f32_e32 v80, 0xbfb8aa3b, v67
	v_mul_f32_e32 v81, 0xbfb8aa3b, v73
	v_mul_f32_e32 v82, 0xbfb8aa3b, v77
	v_mul_f32_e32 v83, 0xbfb8aa3b, v75
	v_mul_f32_e32 v86, 0xbfb8aa3b, v79
	v_mul_f32_e32 v87, 0xbfb8aa3b, v69
	v_mul_f32_e32 v88, 0xbfb8aa3b, v65
	v_mul_f32_e32 v89, 0xbfb8aa3b, v71
	v_exp_f32_e32 v80, v80
	v_exp_f32_e32 v81, v81
	v_exp_f32_e32 v82, v82
	v_exp_f32_e32 v83, v83
	v_exp_f32_e32 v86, v86
	v_exp_f32_e32 v87, v87
	v_exp_f32_e32 v88, v88
	v_exp_f32_e32 v89, v89
	v_add_f32_e32 v80, 1.0, v80
	v_add_f32_e32 v81, 1.0, v81
	v_add_f32_e32 v82, 1.0, v82
	v_add_f32_e32 v83, 1.0, v83
	v_add_f32_e32 v86, 1.0, v86
	v_add_f32_e32 v87, 1.0, v87
	v_add_f32_e32 v88, 1.0, v88
	v_add_f32_e32 v89, 1.0, v89
	v_rcp_f32_e32 v80, v80
	v_rcp_f32_e32 v81, v81
	v_rcp_f32_e32 v82, v82
	v_rcp_f32_e32 v83, v83
	v_rcp_f32_e32 v86, v86
	v_rcp_f32_e32 v87, v87
	v_rcp_f32_e32 v88, v88
	v_rcp_f32_e32 v89, v89
	v_mul_f32_e32 v67, v67, v80
	v_mul_f32_e32 v73, v73, v81
	v_mul_f32_e32 v77, v77, v82
	v_mul_f32_e32 v75, v75, v83
	v_mul_f32_e32 v79, v79, v86
	v_mul_f32_e32 v69, v69, v87
	v_mul_f32_e32 v65, v65, v88
	v_mul_f32_e32 v71, v71, v89
	v_mul_f32_e32 v66, v66, v67
	v_mul_f32_e32 v67, v72, v73
	v_mul_f32_e32 v72, v76, v77
	v_mul_f32_e32 v73, v74, v75
	v_mul_f32_e32 v74, v78, v79
	v_mul_f32_e32 v68, v68, v69
	v_mul_f32_e32 v69, v64, v65
	v_mul_f32_e32 v70, v70, v71
	v_cvt_pk_bf16_f32 v64, v66, v67
	v_cvt_pk_bf16_f32 v65, v72, v73
	v_cvt_pk_bf16_f32 v66, v74, v68
	v_cvt_pk_bf16_f32 v67, v69, v70
	global_store_dwordx4 v[84:85], v[64:67], off
	s_nop 1
	s_nop 0
	v_mov_b32_e32 v66, v60
	v_mov_b32_e32 v60, v62
	v_mov_b32_e32 v62, v48
	v_mov_b32_e32 v48, v50
	v_add_u32_e32 v50, 0x80, v144
	v_mov_b32_e32 v67, v56
	v_mov_b32_e32 v56, v61
	v_mov_b32_e32 v61, v58
	v_mov_b32_e32 v58, v63
	v_mov_b32_e32 v63, v52
	v_mov_b32_e32 v52, v49
	v_mov_b32_e32 v49, v54
	v_mov_b32_e32 v54, v51
	v_mad_i64_i32 v[50:51], s[38:39], v50, s58, v[116:117]
	v_lshl_add_u64 v[68:69], v[50:51], 0, v[118:119]
	v_mov_b32_e32 v64, v230
	v_pk_mul_f32 v[50:51], v[66:67], v[64:65] op_sel_hi:[1,0]
	v_pk_mul_f32 v[56:57], v[56:57], v[64:65] op_sel_hi:[1,0]
	v_pk_mul_f32 v[60:61], v[60:61], v[64:65] op_sel_hi:[1,0]
	v_pk_mul_f32 v[58:59], v[58:59], v[64:65] op_sel_hi:[1,0]
	v_pk_mul_f32 v[62:63], v[62:63], v[64:65] op_sel_hi:[1,0]
	v_pk_mul_f32 v[52:53], v[52:53], v[64:65] op_sel_hi:[1,0]
	v_pk_mul_f32 v[48:49], v[48:49], v[64:65] op_sel_hi:[1,0]
	v_pk_mul_f32 v[54:55], v[54:55], v[64:65] op_sel_hi:[1,0]
	v_mul_f32_e32 v64, 0xbfb8aa3b, v51
	v_mul_f32_e32 v65, 0xbfb8aa3b, v57
	v_mul_f32_e32 v66, 0xbfb8aa3b, v61
	v_mul_f32_e32 v67, 0xbfb8aa3b, v59
	v_mul_f32_e32 v70, 0xbfb8aa3b, v63
	v_mul_f32_e32 v71, 0xbfb8aa3b, v53
	v_mul_f32_e32 v72, 0xbfb8aa3b, v49
	v_mul_f32_e32 v73, 0xbfb8aa3b, v55
	v_exp_f32_e32 v64, v64
	v_exp_f32_e32 v65, v65
	v_exp_f32_e32 v66, v66
	v_exp_f32_e32 v67, v67
	v_exp_f32_e32 v70, v70
	v_exp_f32_e32 v71, v71
	v_exp_f32_e32 v72, v72
	v_exp_f32_e32 v73, v73
	v_add_f32_e32 v64, 1.0, v64
	v_add_f32_e32 v65, 1.0, v65
	v_add_f32_e32 v66, 1.0, v66
	v_add_f32_e32 v67, 1.0, v67
	v_add_f32_e32 v70, 1.0, v70
	v_add_f32_e32 v71, 1.0, v71
	v_add_f32_e32 v72, 1.0, v72
	v_add_f32_e32 v73, 1.0, v73
	v_rcp_f32_e32 v64, v64
	v_rcp_f32_e32 v65, v65
	v_rcp_f32_e32 v66, v66
	v_rcp_f32_e32 v67, v67
	v_rcp_f32_e32 v70, v70
	v_rcp_f32_e32 v71, v71
	v_rcp_f32_e32 v72, v72
	v_rcp_f32_e32 v73, v73
	v_mul_f32_e32 v51, v51, v64
	v_mul_f32_e32 v57, v57, v65
	v_mul_f32_e32 v61, v61, v66
	v_mul_f32_e32 v59, v59, v67
	v_mul_f32_e32 v63, v63, v70
	v_mul_f32_e32 v53, v53, v71
	v_mul_f32_e32 v49, v49, v72
	v_mul_f32_e32 v55, v55, v73
	v_mul_f32_e32 v50, v50, v51
	v_mul_f32_e32 v51, v56, v57
	v_mul_f32_e32 v56, v60, v61
	v_mul_f32_e32 v57, v58, v59
	v_mul_f32_e32 v58, v62, v63
	v_mul_f32_e32 v52, v52, v53
	v_mul_f32_e32 v53, v48, v49
	v_mul_f32_e32 v54, v54, v55
	v_cvt_pk_bf16_f32 v48, v50, v51
	v_cvt_pk_bf16_f32 v49, v56, v57
	v_cvt_pk_bf16_f32 v50, v58, v52
	v_cvt_pk_bf16_f32 v51, v53, v54
	global_store_dwordx4 v[68:69], v[48:51], off
	s_nop 1
	s_nop 0
	v_mov_b32_e32 v50, v44
	v_mov_b32_e32 v44, v46
	v_mov_b32_e32 v46, v32
	v_mov_b32_e32 v32, v34
	v_add_u32_e32 v34, 0x90, v144
	v_mov_b32_e32 v51, v40
	v_mov_b32_e32 v40, v45
	v_mov_b32_e32 v45, v42
	v_mov_b32_e32 v42, v47
	v_mov_b32_e32 v47, v36
	v_mov_b32_e32 v36, v33
	v_mov_b32_e32 v33, v38
	v_mov_b32_e32 v38, v35
	v_mad_i64_i32 v[34:35], s[38:39], v34, s58, v[116:117]
	v_lshl_add_u64 v[52:53], v[34:35], 0, v[118:119]
	v_mov_b32_e32 v48, v231
	v_pk_mul_f32 v[34:35], v[50:51], v[48:49] op_sel_hi:[1,0]
	v_pk_mul_f32 v[40:41], v[40:41], v[48:49] op_sel_hi:[1,0]
	v_pk_mul_f32 v[44:45], v[44:45], v[48:49] op_sel_hi:[1,0]
	v_pk_mul_f32 v[42:43], v[42:43], v[48:49] op_sel_hi:[1,0]
	v_pk_mul_f32 v[46:47], v[46:47], v[48:49] op_sel_hi:[1,0]
	v_pk_mul_f32 v[36:37], v[36:37], v[48:49] op_sel_hi:[1,0]
	v_pk_mul_f32 v[32:33], v[32:33], v[48:49] op_sel_hi:[1,0]
	v_pk_mul_f32 v[38:39], v[38:39], v[48:49] op_sel_hi:[1,0]
	v_mul_f32_e32 v48, 0xbfb8aa3b, v35
	v_mul_f32_e32 v49, 0xbfb8aa3b, v41
	v_mul_f32_e32 v50, 0xbfb8aa3b, v45
	v_mul_f32_e32 v51, 0xbfb8aa3b, v43
	v_mul_f32_e32 v54, 0xbfb8aa3b, v47
	v_mul_f32_e32 v55, 0xbfb8aa3b, v37
	v_mul_f32_e32 v56, 0xbfb8aa3b, v33
	v_mul_f32_e32 v57, 0xbfb8aa3b, v39
	v_exp_f32_e32 v48, v48
	v_exp_f32_e32 v49, v49
	v_exp_f32_e32 v50, v50
	v_exp_f32_e32 v51, v51
	v_exp_f32_e32 v54, v54
	v_exp_f32_e32 v55, v55
	v_exp_f32_e32 v56, v56
	v_exp_f32_e32 v57, v57
	v_add_f32_e32 v48, 1.0, v48
	v_add_f32_e32 v49, 1.0, v49
	v_add_f32_e32 v50, 1.0, v50
	v_add_f32_e32 v51, 1.0, v51
	v_add_f32_e32 v54, 1.0, v54
	v_add_f32_e32 v55, 1.0, v55
	v_add_f32_e32 v56, 1.0, v56
	v_add_f32_e32 v57, 1.0, v57
	v_rcp_f32_e32 v48, v48
	v_rcp_f32_e32 v49, v49
	v_rcp_f32_e32 v50, v50
	v_rcp_f32_e32 v51, v51
	v_rcp_f32_e32 v54, v54
	v_rcp_f32_e32 v55, v55
	v_rcp_f32_e32 v56, v56
	v_rcp_f32_e32 v57, v57
	v_mul_f32_e32 v35, v35, v48
	v_mul_f32_e32 v41, v41, v49
	v_mul_f32_e32 v45, v45, v50
	v_mul_f32_e32 v43, v43, v51
	v_mul_f32_e32 v47, v47, v54
	v_mul_f32_e32 v37, v37, v55
	v_mul_f32_e32 v33, v33, v56
	v_mul_f32_e32 v39, v39, v57
	v_mul_f32_e32 v34, v34, v35
	v_mul_f32_e32 v35, v40, v41
	v_mul_f32_e32 v40, v44, v45
	v_mul_f32_e32 v41, v42, v43
	v_mul_f32_e32 v42, v46, v47
	v_mul_f32_e32 v36, v36, v37
	v_mul_f32_e32 v37, v32, v33
	v_mul_f32_e32 v38, v38, v39
	v_cvt_pk_bf16_f32 v32, v34, v35
	v_cvt_pk_bf16_f32 v33, v40, v41
	v_cvt_pk_bf16_f32 v34, v42, v36
	v_cvt_pk_bf16_f32 v35, v37, v38
	global_store_dwordx4 v[52:53], v[32:35], off
	s_nop 1
	s_nop 0
	v_mov_b32_e32 v34, v28
	v_mov_b32_e32 v28, v30
	v_mov_b32_e32 v30, v16
	v_mov_b32_e32 v16, v18
	v_add_u32_e32 v18, 0xa0, v144
	v_mov_b32_e32 v35, v24
	v_mov_b32_e32 v24, v29
	v_mov_b32_e32 v29, v26
	v_mov_b32_e32 v26, v31
	v_mov_b32_e32 v31, v20
	v_mov_b32_e32 v20, v17
	v_mov_b32_e32 v17, v22
	v_mov_b32_e32 v22, v19
	v_mad_i64_i32 v[18:19], s[38:39], v18, s58, v[116:117]
	v_lshl_add_u64 v[36:37], v[18:19], 0, v[118:119]
	v_mov_b32_e32 v32, v232
	v_pk_mul_f32 v[18:19], v[34:35], v[32:33] op_sel_hi:[1,0]
	v_pk_mul_f32 v[24:25], v[24:25], v[32:33] op_sel_hi:[1,0]
	v_pk_mul_f32 v[28:29], v[28:29], v[32:33] op_sel_hi:[1,0]
	v_pk_mul_f32 v[26:27], v[26:27], v[32:33] op_sel_hi:[1,0]
	v_pk_mul_f32 v[30:31], v[30:31], v[32:33] op_sel_hi:[1,0]
	v_pk_mul_f32 v[20:21], v[20:21], v[32:33] op_sel_hi:[1,0]
	v_pk_mul_f32 v[16:17], v[16:17], v[32:33] op_sel_hi:[1,0]
	v_pk_mul_f32 v[22:23], v[22:23], v[32:33] op_sel_hi:[1,0]
	v_mul_f32_e32 v32, 0xbfb8aa3b, v19
	v_mul_f32_e32 v33, 0xbfb8aa3b, v25
	v_mul_f32_e32 v34, 0xbfb8aa3b, v29
	v_mul_f32_e32 v35, 0xbfb8aa3b, v27
	v_mul_f32_e32 v38, 0xbfb8aa3b, v31
	v_mul_f32_e32 v39, 0xbfb8aa3b, v21
	v_mul_f32_e32 v40, 0xbfb8aa3b, v17
	v_mul_f32_e32 v41, 0xbfb8aa3b, v23
	v_exp_f32_e32 v32, v32
	v_exp_f32_e32 v33, v33
	v_exp_f32_e32 v34, v34
	v_exp_f32_e32 v35, v35
	v_exp_f32_e32 v38, v38
	v_exp_f32_e32 v39, v39
	v_exp_f32_e32 v40, v40
	v_exp_f32_e32 v41, v41
	v_add_f32_e32 v32, 1.0, v32
	v_add_f32_e32 v33, 1.0, v33
	v_add_f32_e32 v34, 1.0, v34
	v_add_f32_e32 v35, 1.0, v35
	v_add_f32_e32 v38, 1.0, v38
	v_add_f32_e32 v39, 1.0, v39
	v_add_f32_e32 v40, 1.0, v40
	v_add_f32_e32 v41, 1.0, v41
	v_rcp_f32_e32 v32, v32
	v_rcp_f32_e32 v33, v33
	v_rcp_f32_e32 v34, v34
	v_rcp_f32_e32 v35, v35
	v_rcp_f32_e32 v38, v38
	v_rcp_f32_e32 v39, v39
	v_rcp_f32_e32 v40, v40
	v_rcp_f32_e32 v41, v41
	v_mul_f32_e32 v19, v19, v32
	v_mul_f32_e32 v25, v25, v33
	v_mul_f32_e32 v29, v29, v34
	v_mul_f32_e32 v27, v27, v35
	v_mul_f32_e32 v31, v31, v38
	v_mul_f32_e32 v21, v21, v39
	v_mul_f32_e32 v17, v17, v40
	v_mul_f32_e32 v23, v23, v41
	v_mul_f32_e32 v18, v18, v19
	v_mul_f32_e32 v19, v24, v25
	v_mul_f32_e32 v24, v28, v29
	v_mul_f32_e32 v25, v26, v27
	v_mul_f32_e32 v26, v30, v31
	v_mul_f32_e32 v20, v20, v21
	v_mul_f32_e32 v21, v16, v17
	v_mul_f32_e32 v22, v22, v23
	v_cvt_pk_bf16_f32 v16, v18, v19
	v_cvt_pk_bf16_f32 v17, v24, v25
	v_cvt_pk_bf16_f32 v18, v26, v20
	v_cvt_pk_bf16_f32 v19, v21, v22
	global_store_dwordx4 v[36:37], v[16:19], off
	s_nop 1
	s_nop 0
	v_mov_b32_e32 v18, v12
	v_mov_b32_e32 v12, v14
	v_mov_b32_e32 v14, v0
	v_mov_b32_e32 v0, v2
	v_add_u32_e32 v2, 0xb0, v144
	v_mov_b32_e32 v19, v8
	v_mov_b32_e32 v8, v13
	v_mov_b32_e32 v13, v10
	v_mov_b32_e32 v10, v15
	v_mov_b32_e32 v15, v4
	v_mov_b32_e32 v4, v1
	v_mov_b32_e32 v1, v6
	v_mov_b32_e32 v6, v3
	v_mad_i64_i32 v[2:3], s[38:39], v2, s58, v[116:117]
	v_lshl_add_u64 v[20:21], v[2:3], 0, v[118:119]
	v_mov_b32_e32 v16, v233
	v_pk_mul_f32 v[2:3], v[18:19], v[16:17] op_sel_hi:[1,0]
	v_pk_mul_f32 v[8:9], v[8:9], v[16:17] op_sel_hi:[1,0]
	v_pk_mul_f32 v[12:13], v[12:13], v[16:17] op_sel_hi:[1,0]
	v_pk_mul_f32 v[10:11], v[10:11], v[16:17] op_sel_hi:[1,0]
	v_pk_mul_f32 v[14:15], v[14:15], v[16:17] op_sel_hi:[1,0]
	v_pk_mul_f32 v[4:5], v[4:5], v[16:17] op_sel_hi:[1,0]
	v_pk_mul_f32 v[0:1], v[0:1], v[16:17] op_sel_hi:[1,0]
	v_pk_mul_f32 v[6:7], v[6:7], v[16:17] op_sel_hi:[1,0]
	v_mul_f32_e32 v16, 0xbfb8aa3b, v3
	v_mul_f32_e32 v17, 0xbfb8aa3b, v9
	v_mul_f32_e32 v18, 0xbfb8aa3b, v13
	v_mul_f32_e32 v19, 0xbfb8aa3b, v11
	v_mul_f32_e32 v22, 0xbfb8aa3b, v15
	v_mul_f32_e32 v23, 0xbfb8aa3b, v5
	v_mul_f32_e32 v24, 0xbfb8aa3b, v1
	v_mul_f32_e32 v25, 0xbfb8aa3b, v7
	v_exp_f32_e32 v16, v16
	v_exp_f32_e32 v17, v17
	v_exp_f32_e32 v18, v18
	v_exp_f32_e32 v19, v19
	v_exp_f32_e32 v22, v22
	v_exp_f32_e32 v23, v23
	v_exp_f32_e32 v24, v24
	v_exp_f32_e32 v25, v25
	v_add_f32_e32 v16, 1.0, v16
	v_add_f32_e32 v17, 1.0, v17
	v_add_f32_e32 v18, 1.0, v18
	v_add_f32_e32 v19, 1.0, v19
	v_add_f32_e32 v22, 1.0, v22
	v_add_f32_e32 v23, 1.0, v23
	v_add_f32_e32 v24, 1.0, v24
	v_add_f32_e32 v25, 1.0, v25
	v_rcp_f32_e32 v16, v16
	v_rcp_f32_e32 v17, v17
	v_rcp_f32_e32 v18, v18
	v_rcp_f32_e32 v19, v19
	v_rcp_f32_e32 v22, v22
	v_rcp_f32_e32 v23, v23
	v_rcp_f32_e32 v24, v24
	v_rcp_f32_e32 v25, v25
	v_mul_f32_e32 v3, v3, v16
	v_mul_f32_e32 v9, v9, v17
	v_mul_f32_e32 v13, v13, v18
	v_mul_f32_e32 v11, v11, v19
	v_mul_f32_e32 v15, v15, v22
	v_mul_f32_e32 v5, v5, v23
	v_mul_f32_e32 v1, v1, v24
	v_mul_f32_e32 v7, v7, v25
	v_mul_f32_e32 v2, v2, v3
	v_mul_f32_e32 v3, v8, v9
	v_mul_f32_e32 v8, v12, v13
	v_mul_f32_e32 v9, v10, v11
	v_mul_f32_e32 v10, v14, v15
	v_mul_f32_e32 v4, v4, v5
	v_mul_f32_e32 v5, v0, v1
	v_mul_f32_e32 v6, v6, v7
	v_cvt_pk_bf16_f32 v0, v2, v3
	v_cvt_pk_bf16_f32 v1, v8, v9
	v_cvt_pk_bf16_f32 v2, v10, v4
	v_cvt_pk_bf16_f32 v3, v5, v6
	global_store_dwordx4 v[20:21], v[0:3], off
	s_cbranch_vccnz .LBB0_1304
	s_andn2_b64 vcc, exec, s[14:15]
	s_cbranch_vccnz .LBB0_1303
	s_barrier
	s_branch .LBB0_1303
